# intermediate loads after P3 default-cached instead of nt (192 loads)
# baseline (speedup 1.0000x reference)
.LBB0_964:
	s_add_i32 s7, s12, s18
	s_add_i32 s6, s7, 0xffffb000
	s_cmpk_gt_i32 s6, 0x1ff
	s_mov_b64 s[4:5], -1
	s_cbranch_scc0 .LBB0_974
	s_cmpk_gt_u32 s6, 0x5ff
	s_cbranch_scc0 .LBB0_971
	s_and_b32 s19, s13, 0x7e0
	s_cmpk_gt_u32 s6, 0x9ff
	v_or_b32_e32 v21, s19, v24
	v_or_b32_e32 v20, s19, v26
	v_or_b32_e32 v19, s19, v27
	v_or_b32_e32 v18, s19, v28
	s_cbranch_scc0 .LBB0_968
	s_and_b32 s2, s6, 0x7fffffc0
	s_add_i32 s4, s2, 0xfffff600
	v_or_b32_e32 v0, s4, v22
	s_lshl_b32 s2, s19, 2
	v_lshl_add_u64 v[36:37], v[2:3], 0, s[2:3]
	v_lshlrev_b64 v[38:39], 13, v[0:1]
	v_or_b32_e32 v40, 2, v0
	v_mov_b32_e32 v41, v1
	v_or_b32_e32 v42, 4, v0
	v_mov_b32_e32 v43, v1
	v_or_b32_e32 v44, 6, v0
	v_mov_b32_e32 v45, v1
	v_or_b32_e32 v46, 8, v0
	v_mov_b32_e32 v47, v1
	v_or_b32_e32 v48, 10, v0
	v_mov_b32_e32 v49, v1
	v_or_b32_e32 v50, 12, v0
	v_mov_b32_e32 v51, v1
	v_or_b32_e32 v52, 14, v0
	v_mov_b32_e32 v53, v1
	v_lshl_add_u64 v[38:39], v[36:37], 0, v[38:39]
	v_lshlrev_b64 v[40:41], 13, v[40:41]
	v_lshlrev_b64 v[42:43], 13, v[42:43]
	v_lshlrev_b64 v[44:45], 13, v[44:45]
	v_lshlrev_b64 v[46:47], 13, v[46:47]
	v_lshlrev_b64 v[48:49], 13, v[48:49]
	v_lshlrev_b64 v[50:51], 13, v[50:51]
	v_lshlrev_b64 v[52:53], 13, v[52:53]
	v_lshl_add_u64 v[40:41], v[36:37], 0, v[40:41]
	v_lshl_add_u64 v[42:43], v[36:37], 0, v[42:43]
	v_lshl_add_u64 v[44:45], v[36:37], 0, v[44:45]
	v_lshl_add_u64 v[46:47], v[36:37], 0, v[46:47]
	v_lshl_add_u64 v[48:49], v[36:37], 0, v[48:49]
	v_lshl_add_u64 v[50:51], v[36:37], 0, v[50:51]
	v_lshl_add_u64 v[52:53], v[36:37], 0, v[52:53]
	global_load_dword v54, v[38:39], off
	global_load_dword v55, v[40:41], off
	global_load_dword v56, v[42:43], off
	global_load_dword v57, v[44:45], off
	global_load_dword v58, v[46:47], off
	global_load_dword v59, v[48:49], off
	global_load_dword v60, v[50:51], off
	global_load_dword v61, v[52:53], off
	v_or_b32_e32 v38, 16, v0
	v_mov_b32_e32 v39, v1
	v_lshlrev_b64 v[38:39], 13, v[38:39]
	v_or_b32_e32 v40, 18, v0
	v_mov_b32_e32 v41, v1
	v_or_b32_e32 v42, 20, v0
	v_mov_b32_e32 v43, v1
	v_or_b32_e32 v44, 22, v0
	v_mov_b32_e32 v45, v1
	v_or_b32_e32 v46, 24, v0
	v_mov_b32_e32 v47, v1
	v_or_b32_e32 v48, 26, v0
	v_mov_b32_e32 v49, v1
	v_or_b32_e32 v50, 28, v0
	v_mov_b32_e32 v51, v1
	v_or_b32_e32 v52, 30, v0
	v_mov_b32_e32 v53, v1
	v_lshl_add_u64 v[38:39], v[36:37], 0, v[38:39]
	v_lshlrev_b64 v[40:41], 13, v[40:41]
	v_lshlrev_b64 v[42:43], 13, v[42:43]
	v_lshlrev_b64 v[44:45], 13, v[44:45]
	v_lshlrev_b64 v[46:47], 13, v[46:47]
	v_lshlrev_b64 v[48:49], 13, v[48:49]
	v_lshlrev_b64 v[50:51], 13, v[50:51]
	v_lshlrev_b64 v[52:53], 13, v[52:53]
	v_lshl_add_u64 v[40:41], v[36:37], 0, v[40:41]
	v_lshl_add_u64 v[42:43], v[36:37], 0, v[42:43]
	v_lshl_add_u64 v[44:45], v[36:37], 0, v[44:45]
	v_lshl_add_u64 v[46:47], v[36:37], 0, v[46:47]
	v_lshl_add_u64 v[48:49], v[36:37], 0, v[48:49]
	v_lshl_add_u64 v[50:51], v[36:37], 0, v[50:51]
	v_lshl_add_u64 v[52:53], v[36:37], 0, v[52:53]
	global_load_dword v62, v[38:39], off
	global_load_dword v63, v[40:41], off
	global_load_dword v64, v[42:43], off
	global_load_dword v65, v[44:45], off
	global_load_dword v66, v[46:47], off
	global_load_dword v67, v[48:49], off
	global_load_dword v68, v[50:51], off
	global_load_dword v69, v[52:53], off
	v_or_b32_e32 v38, 32, v0
	v_mov_b32_e32 v39, v1
	v_lshlrev_b64 v[38:39], 13, v[38:39]
	v_or_b32_e32 v40, 34, v0
	v_mov_b32_e32 v41, v1
	v_or_b32_e32 v42, 36, v0
	v_mov_b32_e32 v43, v1
	v_or_b32_e32 v44, 38, v0
	v_mov_b32_e32 v45, v1
	v_or_b32_e32 v46, 40, v0
	v_mov_b32_e32 v47, v1
	v_or_b32_e32 v48, 42, v0
	v_mov_b32_e32 v49, v1
	v_or_b32_e32 v50, 44, v0
	v_mov_b32_e32 v51, v1
	v_or_b32_e32 v52, 46, v0
	v_mov_b32_e32 v53, v1
	v_lshl_add_u64 v[38:39], v[36:37], 0, v[38:39]
	v_lshlrev_b64 v[40:41], 13, v[40:41]
	v_lshlrev_b64 v[42:43], 13, v[42:43]
	v_lshlrev_b64 v[44:45], 13, v[44:45]
	v_lshlrev_b64 v[46:47], 13, v[46:47]
	v_lshlrev_b64 v[48:49], 13, v[48:49]
	v_lshlrev_b64 v[50:51], 13, v[50:51]
	v_lshlrev_b64 v[52:53], 13, v[52:53]
	v_lshl_add_u64 v[40:41], v[36:37], 0, v[40:41]
	v_lshl_add_u64 v[42:43], v[36:37], 0, v[42:43]
	v_lshl_add_u64 v[44:45], v[36:37], 0, v[44:45]
	v_lshl_add_u64 v[46:47], v[36:37], 0, v[46:47]
	v_lshl_add_u64 v[48:49], v[36:37], 0, v[48:49]
	v_lshl_add_u64 v[50:51], v[36:37], 0, v[50:51]
	v_lshl_add_u64 v[52:53], v[36:37], 0, v[52:53]
	global_load_dword v70, v[38:39], off
	global_load_dword v71, v[40:41], off
	global_load_dword v72, v[42:43], off
	global_load_dword v73, v[44:45], off
	global_load_dword v74, v[46:47], off
	global_load_dword v75, v[48:49], off
	global_load_dword v76, v[50:51], off
	global_load_dword v77, v[52:53], off
	v_or_b32_e32 v38, 48, v0
	v_mov_b32_e32 v39, v1
	v_lshlrev_b64 v[38:39], 13, v[38:39]
	v_or_b32_e32 v40, 50, v0
	v_mov_b32_e32 v41, v1
	v_or_b32_e32 v42, 52, v0
	v_mov_b32_e32 v43, v1
	v_or_b32_e32 v44, 54, v0
	v_mov_b32_e32 v45, v1
	v_or_b32_e32 v46, 56, v0
	v_mov_b32_e32 v47, v1
	v_or_b32_e32 v48, 58, v0
	v_mov_b32_e32 v49, v1
	v_or_b32_e32 v50, 60, v0
	v_mov_b32_e32 v51, v1
	v_or_b32_e32 v0, 62, v0
	v_lshl_add_u64 v[38:39], v[36:37], 0, v[38:39]
	v_lshlrev_b64 v[40:41], 13, v[40:41]
	v_lshlrev_b64 v[42:43], 13, v[42:43]
	v_lshlrev_b64 v[44:45], 13, v[44:45]
	v_lshlrev_b64 v[46:47], 13, v[46:47]
	v_lshlrev_b64 v[48:49], 13, v[48:49]
	v_lshlrev_b64 v[50:51], 13, v[50:51]
	v_lshlrev_b64 v[52:53], 13, v[0:1]
	v_lshl_add_u64 v[40:41], v[36:37], 0, v[40:41]
	v_lshl_add_u64 v[42:43], v[36:37], 0, v[42:43]
	v_lshl_add_u64 v[44:45], v[36:37], 0, v[44:45]
	v_lshl_add_u64 v[46:47], v[36:37], 0, v[46:47]
	v_lshl_add_u64 v[48:49], v[36:37], 0, v[48:49]
	v_lshl_add_u64 v[50:51], v[36:37], 0, v[50:51]
	v_lshl_add_u64 v[36:37], v[36:37], 0, v[52:53]
	global_load_dword v0, v[38:39], off
	global_load_dword v52, v[40:41], off
	global_load_dword v53, v[42:43], off
	global_load_dword v78, v[44:45], off
	global_load_dword v79, v[46:47], off
	global_load_dword v80, v[48:49], off
	global_load_dword v81, v[50:51], off
	global_load_dword v82, v[36:37], off
	s_waitcnt vmcnt(30)
	ds_write2_b32 v23, v54, v55 offset1:66
	s_waitcnt vmcnt(28)
	ds_write2_b32 v23, v56, v57 offset0:132 offset1:198
	s_waitcnt vmcnt(26)
	ds_write2_b32 v29, v58, v59 offset0:8 offset1:74
	s_waitcnt vmcnt(24)
	ds_write2_b32 v29, v60, v61 offset0:140 offset1:206
	s_waitcnt vmcnt(22)
	ds_write2_b32 v30, v62, v63 offset0:16 offset1:82
	s_waitcnt vmcnt(20)
	ds_write2_b32 v30, v64, v65 offset0:148 offset1:214
	s_waitcnt vmcnt(18)
	ds_write2_b32 v31, v66, v67 offset0:24 offset1:90
	s_waitcnt vmcnt(16)
	ds_write2_b32 v31, v68, v69 offset0:156 offset1:222
	s_waitcnt vmcnt(14)
	ds_write2_b32 v32, v70, v71 offset0:32 offset1:98
	s_waitcnt vmcnt(12)
	ds_write2_b32 v32, v72, v73 offset0:164 offset1:230
	s_waitcnt vmcnt(10)
	ds_write2_b32 v33, v74, v75 offset0:40 offset1:106
	s_waitcnt vmcnt(8)
	ds_write2_b32 v33, v76, v77 offset0:172 offset1:238
	s_waitcnt vmcnt(6)
	ds_write2_b32 v34, v0, v52 offset0:48 offset1:114
	s_waitcnt vmcnt(4)
	ds_write2_b32 v34, v53, v78 offset0:180 offset1:246
	s_waitcnt vmcnt(2)
	ds_write2_b32 v35, v79, v80 offset0:56 offset1:122
	s_waitcnt vmcnt(0)
	ds_write2_b32 v35, v81, v82 offset0:188 offset1:254
	s_waitcnt lgkmcnt(0)
	ds_read2_b32 v[40:41], v25 offset0:33 offset1:41
	ds_read2_b32 v[42:43], v25 offset1:8
	ds_read2_b32 v[44:45], v25 offset0:66 offset1:74
	ds_read2_b32 v[46:47], v25 offset0:99 offset1:107
	ds_read2_b32 v[48:49], v25 offset0:132 offset1:140
	ds_read2_b32 v[50:51], v25 offset0:165 offset1:173
	ds_read2_b32 v[52:53], v25 offset0:198 offset1:206
	ds_read2_b32 v[54:55], v25 offset0:231 offset1:239
	s_mov_b32 s5, s3
	v_lshl_add_u64 v[56:57], s[4:5], 1, v[4:5]
	v_lshlrev_b32_e32 v0, 12, v21
	s_waitcnt lgkmcnt(6)
	v_cvt_pk_bf16_f32 v36, v42, v40
	s_waitcnt lgkmcnt(4)
	v_cvt_pk_bf16_f32 v37, v44, v46
	s_waitcnt lgkmcnt(2)
	v_cvt_pk_bf16_f32 v38, v48, v50
	s_waitcnt lgkmcnt(0)
	v_cvt_pk_bf16_f32 v39, v52, v54
	v_lshl_add_u64 v[58:59], v[56:57], 0, v[0:1]
	global_store_dwordx4 v[58:59], v[36:39], off
	v_lshlrev_b32_e32 v0, 12, v20
	s_mov_b64 s[4:5], 0
	v_cvt_pk_bf16_f32 v36, v43, v41
	v_cvt_pk_bf16_f32 v37, v45, v47
	v_cvt_pk_bf16_f32 v38, v49, v51
	v_cvt_pk_bf16_f32 v39, v53, v55
	ds_read2_b32 v[42:43], v25 offset0:49 offset1:57
	ds_read2_b32 v[44:45], v25 offset0:16 offset1:24
	ds_read2_b32 v[46:47], v25 offset0:82 offset1:90
	ds_read2_b32 v[48:49], v25 offset0:115 offset1:123
	ds_read2_b32 v[50:51], v25 offset0:148 offset1:156
	ds_read2_b32 v[52:53], v25 offset0:181 offset1:189
	ds_read2_b32 v[54:55], v25 offset0:214 offset1:222
	ds_read2_b32 v[58:59], v25 offset0:247 offset1:255
	v_lshl_add_u64 v[40:41], v[56:57], 0, v[0:1]
	v_lshlrev_b32_e32 v0, 12, v19
	global_store_dwordx4 v[40:41], v[36:39], off
	v_lshl_add_u64 v[40:41], v[56:57], 0, v[0:1]
	v_lshlrev_b32_e32 v0, 12, v18
	s_waitcnt lgkmcnt(6)
	v_cvt_pk_bf16_f32 v36, v44, v42
	s_waitcnt lgkmcnt(4)
	v_cvt_pk_bf16_f32 v37, v46, v48
	s_waitcnt lgkmcnt(2)
	v_cvt_pk_bf16_f32 v38, v50, v52
	s_waitcnt lgkmcnt(0)
	v_cvt_pk_bf16_f32 v39, v54, v58
	global_store_dwordx4 v[40:41], v[36:39], off
	v_lshl_add_u64 v[40:41], v[56:57], 0, v[0:1]
	s_nop 0
	v_cvt_pk_bf16_f32 v36, v45, v43
	v_cvt_pk_bf16_f32 v37, v47, v49
	v_cvt_pk_bf16_f32 v38, v51, v53
	v_cvt_pk_bf16_f32 v39, v55, v59
	global_store_dwordx4 v[40:41], v[36:39], off
	s_waitcnt lgkmcnt(0)
.LBB0_968:
	s_andn2_b64 vcc, exec, s[4:5]
	s_cbranch_vccnz .LBB0_970
	s_add_i32 s2, s7, 0xaa00
	s_and_b32 s4, s2, 0xffc0
	v_or_b32_e32 v0, s4, v22
	s_lshl_b32 s2, s19, 2
	v_lshl_add_u64 v[36:37], v[6:7], 0, s[2:3]
	v_lshlrev_b32_e32 v0, 13, v0
	v_lshl_add_u64 v[36:37], v[36:37], 0, v[0:1]
	v_add_co_u32_e32 v38, vcc, 0x4000, v36
	s_lshl_b32 s2, s4, 1
	s_nop 0
	v_addc_co_u32_e32 v39, vcc, 0, v37, vcc
	v_add_co_u32_e32 v40, vcc, 0x8000, v36
	s_nop 1
	v_addc_co_u32_e32 v41, vcc, 0, v37, vcc
	v_add_co_u32_e32 v42, vcc, 0xc000, v36
	s_nop 1
	v_addc_co_u32_e32 v43, vcc, 0, v37, vcc
	v_add_co_u32_e32 v44, vcc, 0x10000, v36
	s_nop 1
	v_addc_co_u32_e32 v45, vcc, 0, v37, vcc
	v_add_co_u32_e32 v46, vcc, 0x14000, v36
	s_nop 1
	v_addc_co_u32_e32 v47, vcc, 0, v37, vcc
	v_add_co_u32_e32 v48, vcc, 0x18000, v36
	s_nop 1
	v_addc_co_u32_e32 v49, vcc, 0, v37, vcc
	v_add_co_u32_e32 v50, vcc, 0x1c000, v36
	s_nop 1
	v_addc_co_u32_e32 v51, vcc, 0, v37, vcc
	global_load_dword v0, v[36:37], off
	global_load_dword v54, v[38:39], off
	global_load_dword v55, v[40:41], off
	global_load_dword v56, v[42:43], off
	global_load_dword v57, v[44:45], off
	global_load_dword v58, v[46:47], off
	global_load_dword v59, v[48:49], off
	global_load_dword v60, v[50:51], off
	v_add_co_u32_e32 v38, vcc, 0x20000, v36
	s_nop 1
	v_addc_co_u32_e32 v39, vcc, 0, v37, vcc
	v_add_co_u32_e32 v40, vcc, 0x24000, v36
	s_nop 1
	v_addc_co_u32_e32 v41, vcc, 0, v37, vcc
	v_add_co_u32_e32 v42, vcc, 0x28000, v36
	s_nop 1
	v_addc_co_u32_e32 v43, vcc, 0, v37, vcc
	v_add_co_u32_e32 v44, vcc, 0x2c000, v36
	s_nop 1
	v_addc_co_u32_e32 v45, vcc, 0, v37, vcc
	v_add_co_u32_e32 v46, vcc, 0x30000, v36
	s_nop 1
	v_addc_co_u32_e32 v47, vcc, 0, v37, vcc
	v_add_co_u32_e32 v48, vcc, 0x34000, v36
	s_nop 1
	v_addc_co_u32_e32 v49, vcc, 0, v37, vcc
	v_add_co_u32_e32 v50, vcc, 0x38000, v36
	s_nop 1
	v_addc_co_u32_e32 v51, vcc, 0, v37, vcc
	v_add_co_u32_e32 v52, vcc, 0x3c000, v36
	s_nop 1
	v_addc_co_u32_e32 v53, vcc, 0, v37, vcc
	global_load_dword v61, v[38:39], off
	global_load_dword v62, v[40:41], off
	global_load_dword v63, v[42:43], off
	global_load_dword v64, v[44:45], off
	global_load_dword v65, v[46:47], off
	global_load_dword v66, v[48:49], off
	global_load_dword v67, v[50:51], off
	global_load_dword v68, v[52:53], off
	v_add_co_u32_e32 v38, vcc, 0x40000, v36
	s_nop 1
	v_addc_co_u32_e32 v39, vcc, 0, v37, vcc
	v_add_co_u32_e32 v40, vcc, 0x44000, v36
	s_nop 1
	v_addc_co_u32_e32 v41, vcc, 0, v37, vcc
	v_add_co_u32_e32 v42, vcc, 0x48000, v36
	s_nop 1
	v_addc_co_u32_e32 v43, vcc, 0, v37, vcc
	v_add_co_u32_e32 v44, vcc, 0x4c000, v36
	s_nop 1
	v_addc_co_u32_e32 v45, vcc, 0, v37, vcc
	v_add_co_u32_e32 v46, vcc, 0x50000, v36
	s_nop 1
	v_addc_co_u32_e32 v47, vcc, 0, v37, vcc
	v_add_co_u32_e32 v48, vcc, 0x54000, v36
	s_nop 1
	v_addc_co_u32_e32 v49, vcc, 0, v37, vcc
	v_add_co_u32_e32 v50, vcc, 0x58000, v36
	s_nop 1
	v_addc_co_u32_e32 v51, vcc, 0, v37, vcc
	v_add_co_u32_e32 v52, vcc, 0x5c000, v36
	s_nop 1
	v_addc_co_u32_e32 v53, vcc, 0, v37, vcc
	global_load_dword v69, v[38:39], off
	global_load_dword v70, v[40:41], off
	global_load_dword v71, v[42:43], off
	global_load_dword v72, v[44:45], off
	global_load_dword v73, v[46:47], off
	global_load_dword v74, v[48:49], off
	global_load_dword v75, v[50:51], off
	global_load_dword v76, v[52:53], off
	v_add_co_u32_e32 v38, vcc, 0x60000, v36
	s_nop 1
	v_addc_co_u32_e32 v39, vcc, 0, v37, vcc
	v_add_co_u32_e32 v40, vcc, 0x64000, v36
	s_nop 1
	v_addc_co_u32_e32 v41, vcc, 0, v37, vcc
	v_add_co_u32_e32 v42, vcc, 0x68000, v36
	s_nop 1
	v_addc_co_u32_e32 v43, vcc, 0, v37, vcc
	v_add_co_u32_e32 v44, vcc, 0x6c000, v36
	s_nop 1
	v_addc_co_u32_e32 v45, vcc, 0, v37, vcc
	v_add_co_u32_e32 v46, vcc, 0x70000, v36
	s_nop 1
	v_addc_co_u32_e32 v47, vcc, 0, v37, vcc
	v_add_co_u32_e32 v48, vcc, 0x74000, v36
	s_nop 1
	v_addc_co_u32_e32 v49, vcc, 0, v37, vcc
	v_add_co_u32_e32 v50, vcc, 0x78000, v36
	s_nop 1
	v_addc_co_u32_e32 v51, vcc, 0, v37, vcc
	v_add_co_u32_e32 v36, vcc, 0x7c000, v36
	s_nop 1
	v_addc_co_u32_e32 v37, vcc, 0, v37, vcc
	global_load_dword v52, v[38:39], off
	global_load_dword v53, v[40:41], off
	global_load_dword v77, v[42:43], off
	global_load_dword v78, v[44:45], off
	global_load_dword v79, v[46:47], off
	global_load_dword v80, v[48:49], off
	global_load_dword v81, v[50:51], off
	global_load_dword v82, v[36:37], off
	s_waitcnt vmcnt(30)
	ds_write2_b32 v23, v0, v54 offset1:66
	s_waitcnt vmcnt(28)
	ds_write2_b32 v23, v55, v56 offset0:132 offset1:198
	s_waitcnt vmcnt(26)
	ds_write2_b32 v29, v57, v58 offset0:8 offset1:74
	s_waitcnt vmcnt(24)
	ds_write2_b32 v29, v59, v60 offset0:140 offset1:206
	s_waitcnt vmcnt(22)
	ds_write2_b32 v30, v61, v62 offset0:16 offset1:82
	s_waitcnt vmcnt(20)
	ds_write2_b32 v30, v63, v64 offset0:148 offset1:214
	s_waitcnt vmcnt(18)
	ds_write2_b32 v31, v65, v66 offset0:24 offset1:90
	s_waitcnt vmcnt(16)
	ds_write2_b32 v31, v67, v68 offset0:156 offset1:222
	s_waitcnt vmcnt(14)
	ds_write2_b32 v32, v69, v70 offset0:32 offset1:98
	s_waitcnt vmcnt(12)
	ds_write2_b32 v32, v71, v72 offset0:164 offset1:230
	s_waitcnt vmcnt(10)
	ds_write2_b32 v33, v73, v74 offset0:40 offset1:106
	s_waitcnt vmcnt(8)
	ds_write2_b32 v33, v75, v76 offset0:172 offset1:238
	s_waitcnt vmcnt(6)
	ds_write2_b32 v34, v52, v53 offset0:48 offset1:114
	s_waitcnt vmcnt(4)
	ds_write2_b32 v34, v77, v78 offset0:180 offset1:246
	s_waitcnt vmcnt(2)
	ds_write2_b32 v35, v79, v80 offset0:56 offset1:122
	s_waitcnt vmcnt(0)
	ds_write2_b32 v35, v81, v82 offset0:188 offset1:254
	s_waitcnt lgkmcnt(0)
	ds_read2_b32 v[40:41], v25 offset0:33 offset1:41
	ds_read2_b32 v[42:43], v25 offset1:8
	ds_read2_b32 v[44:45], v25 offset0:66 offset1:74
	ds_read2_b32 v[46:47], v25 offset0:99 offset1:107
	ds_read2_b32 v[48:49], v25 offset0:132 offset1:140
	ds_read2_b32 v[50:51], v25 offset0:165 offset1:173
	ds_read2_b32 v[52:53], v25 offset0:198 offset1:206
	ds_read2_b32 v[54:55], v25 offset0:231 offset1:239
	v_lshl_add_u64 v[56:57], v[8:9], 0, s[2:3]
	v_lshlrev_b32_e32 v0, 12, v21
	s_waitcnt lgkmcnt(6)
	v_cvt_pk_bf16_f32 v36, v42, v40
	s_waitcnt lgkmcnt(4)
	v_cvt_pk_bf16_f32 v37, v44, v46
	s_waitcnt lgkmcnt(2)
	v_cvt_pk_bf16_f32 v38, v48, v50
	s_waitcnt lgkmcnt(0)
	v_cvt_pk_bf16_f32 v39, v52, v54
	v_lshl_add_u64 v[58:59], v[56:57], 0, v[0:1]
	global_store_dwordx4 v[58:59], v[36:39], off
	v_lshlrev_b32_e32 v0, 12, v20
	v_lshl_add_u64 v[20:21], v[56:57], 0, v[0:1]
	v_cvt_pk_bf16_f32 v36, v43, v41
	v_cvt_pk_bf16_f32 v37, v45, v47
	v_cvt_pk_bf16_f32 v38, v49, v51
	v_cvt_pk_bf16_f32 v39, v53, v55
	ds_read2_b32 v[40:41], v25 offset0:49 offset1:57
	ds_read2_b32 v[42:43], v25 offset0:16 offset1:24
	ds_read2_b32 v[44:45], v25 offset0:82 offset1:90
	ds_read2_b32 v[46:47], v25 offset0:115 offset1:123
	ds_read2_b32 v[48:49], v25 offset0:148 offset1:156
	ds_read2_b32 v[50:51], v25 offset0:181 offset1:189
	ds_read2_b32 v[52:53], v25 offset0:214 offset1:222
	ds_read2_b32 v[54:55], v25 offset0:247 offset1:255
	v_lshlrev_b32_e32 v0, 12, v19
	global_store_dwordx4 v[20:21], v[36:39], off
	v_lshl_add_u64 v[20:21], v[56:57], 0, v[0:1]
	v_lshlrev_b32_e32 v0, 12, v18
	s_waitcnt lgkmcnt(6)
	v_cvt_pk_bf16_f32 v36, v42, v40
	s_waitcnt lgkmcnt(4)
	v_cvt_pk_bf16_f32 v37, v44, v46
	s_waitcnt lgkmcnt(2)
	v_cvt_pk_bf16_f32 v38, v48, v50
	s_waitcnt lgkmcnt(0)
	v_cvt_pk_bf16_f32 v39, v52, v54
	global_store_dwordx4 v[20:21], v[36:39], off
	v_lshl_add_u64 v[18:19], v[56:57], 0, v[0:1]
	s_nop 0
	v_cvt_pk_bf16_f32 v36, v43, v41
	v_cvt_pk_bf16_f32 v37, v45, v47
	v_cvt_pk_bf16_f32 v38, v49, v51
	v_cvt_pk_bf16_f32 v39, v53, v55
	global_store_dwordx4 v[18:19], v[36:39], off
	s_waitcnt lgkmcnt(0)

.LBB0_971:
	s_andn2_b64 vcc, exec, s[4:5]
	s_cbranch_vccnz .LBB0_973
	s_add_i32 s7, s7, 0xae00
	s_and_b32 s5, s7, 0xffc0
	s_and_b32 s4, s13, 0x7e0
	v_or_b32_e32 v0, s5, v22
	s_lshl_b32 s2, s4, 2
	v_lshl_add_u64 v[18:19], v[10:11], 0, s[2:3]
	v_lshlrev_b32_e32 v0, 13, v0
	v_lshl_add_u64 v[18:19], v[18:19], 0, v[0:1]
	v_add_co_u32_e32 v20, vcc, 0x4000, v18
	s_lshl_b32 s2, s5, 1
	s_nop 0
	v_addc_co_u32_e32 v21, vcc, 0, v19, vcc
	v_add_co_u32_e32 v36, vcc, 0x8000, v18
	s_nop 1
	v_addc_co_u32_e32 v37, vcc, 0, v19, vcc
	v_add_co_u32_e32 v38, vcc, 0xc000, v18
	s_nop 1
	v_addc_co_u32_e32 v39, vcc, 0, v19, vcc
	v_add_co_u32_e32 v40, vcc, 0x10000, v18
	s_nop 1
	v_addc_co_u32_e32 v41, vcc, 0, v19, vcc
	v_add_co_u32_e32 v42, vcc, 0x14000, v18
	s_nop 1
	v_addc_co_u32_e32 v43, vcc, 0, v19, vcc
	v_add_co_u32_e32 v44, vcc, 0x18000, v18
	s_nop 1
	v_addc_co_u32_e32 v45, vcc, 0, v19, vcc
	v_add_co_u32_e32 v46, vcc, 0x1c000, v18
	s_nop 1
	v_addc_co_u32_e32 v47, vcc, 0, v19, vcc
	global_load_dword v0, v[18:19], off
	global_load_dword v50, v[20:21], off
	global_load_dword v51, v[36:37], off
	global_load_dword v52, v[38:39], off
	global_load_dword v53, v[40:41], off
	global_load_dword v54, v[42:43], off
	global_load_dword v55, v[44:45], off
	global_load_dword v56, v[46:47], off
	v_add_co_u32_e32 v20, vcc, 0x20000, v18
	s_nop 1
	v_addc_co_u32_e32 v21, vcc, 0, v19, vcc
	v_add_co_u32_e32 v36, vcc, 0x24000, v18
	s_nop 1
	v_addc_co_u32_e32 v37, vcc, 0, v19, vcc
	v_add_co_u32_e32 v38, vcc, 0x28000, v18
	s_nop 1
	v_addc_co_u32_e32 v39, vcc, 0, v19, vcc
	v_add_co_u32_e32 v40, vcc, 0x2c000, v18
	s_nop 1
	v_addc_co_u32_e32 v41, vcc, 0, v19, vcc
	v_add_co_u32_e32 v42, vcc, 0x30000, v18
	s_nop 1
	v_addc_co_u32_e32 v43, vcc, 0, v19, vcc
	v_add_co_u32_e32 v44, vcc, 0x34000, v18
	s_nop 1
	v_addc_co_u32_e32 v45, vcc, 0, v19, vcc
	v_add_co_u32_e32 v46, vcc, 0x38000, v18
	s_nop 1
	v_addc_co_u32_e32 v47, vcc, 0, v19, vcc
	v_add_co_u32_e32 v48, vcc, 0x3c000, v18
	s_nop 1
	v_addc_co_u32_e32 v49, vcc, 0, v19, vcc
	global_load_dword v57, v[20:21], off
	global_load_dword v58, v[36:37], off
	global_load_dword v59, v[38:39], off
	global_load_dword v60, v[40:41], off
	global_load_dword v61, v[42:43], off
	global_load_dword v62, v[44:45], off
	global_load_dword v63, v[46:47], off
	global_load_dword v64, v[48:49], off
	v_add_co_u32_e32 v20, vcc, 0x40000, v18
	s_nop 1
	v_addc_co_u32_e32 v21, vcc, 0, v19, vcc
	v_add_co_u32_e32 v36, vcc, 0x44000, v18
	s_nop 1
	v_addc_co_u32_e32 v37, vcc, 0, v19, vcc
	v_add_co_u32_e32 v38, vcc, 0x48000, v18
	s_nop 1
	v_addc_co_u32_e32 v39, vcc, 0, v19, vcc
	v_add_co_u32_e32 v40, vcc, 0x4c000, v18
	s_nop 1
	v_addc_co_u32_e32 v41, vcc, 0, v19, vcc
	v_add_co_u32_e32 v42, vcc, 0x50000, v18
	s_nop 1
	v_addc_co_u32_e32 v43, vcc, 0, v19, vcc
	v_add_co_u32_e32 v44, vcc, 0x54000, v18
	s_nop 1
	v_addc_co_u32_e32 v45, vcc, 0, v19, vcc
	v_add_co_u32_e32 v46, vcc, 0x58000, v18
	s_nop 1
	v_addc_co_u32_e32 v47, vcc, 0, v19, vcc
	v_add_co_u32_e32 v48, vcc, 0x5c000, v18
	s_nop 1
	v_addc_co_u32_e32 v49, vcc, 0, v19, vcc
	global_load_dword v65, v[20:21], off
	global_load_dword v66, v[36:37], off
	global_load_dword v67, v[38:39], off
	global_load_dword v68, v[40:41], off
	global_load_dword v69, v[42:43], off
	global_load_dword v70, v[44:45], off
	global_load_dword v71, v[46:47], off
	global_load_dword v72, v[48:49], off
	v_add_co_u32_e32 v20, vcc, 0x60000, v18
	s_nop 1
	v_addc_co_u32_e32 v21, vcc, 0, v19, vcc
	v_add_co_u32_e32 v36, vcc, 0x64000, v18
	s_nop 1
	v_addc_co_u32_e32 v37, vcc, 0, v19, vcc
	v_add_co_u32_e32 v38, vcc, 0x68000, v18
	s_nop 1
	v_addc_co_u32_e32 v39, vcc, 0, v19, vcc
	v_add_co_u32_e32 v40, vcc, 0x6c000, v18
	s_nop 1
	v_addc_co_u32_e32 v41, vcc, 0, v19, vcc
	v_add_co_u32_e32 v42, vcc, 0x70000, v18
	s_nop 1
	v_addc_co_u32_e32 v43, vcc, 0, v19, vcc
	v_add_co_u32_e32 v44, vcc, 0x74000, v18
	s_nop 1
	v_addc_co_u32_e32 v45, vcc, 0, v19, vcc
	v_add_co_u32_e32 v46, vcc, 0x78000, v18
	s_nop 1
	v_addc_co_u32_e32 v47, vcc, 0, v19, vcc
	v_add_co_u32_e32 v18, vcc, 0x7c000, v18
	s_nop 1
	v_addc_co_u32_e32 v19, vcc, 0, v19, vcc
	global_load_dword v48, v[20:21], off
	global_load_dword v49, v[36:37], off
	global_load_dword v73, v[38:39], off
	global_load_dword v74, v[40:41], off
	global_load_dword v75, v[42:43], off
	global_load_dword v76, v[44:45], off
	global_load_dword v77, v[46:47], off
	global_load_dword v78, v[18:19], off
	s_waitcnt vmcnt(30)
	ds_write2_b32 v23, v0, v50 offset1:66
	s_waitcnt vmcnt(28)
	ds_write2_b32 v23, v51, v52 offset0:132 offset1:198
	s_waitcnt vmcnt(26)
	ds_write2_b32 v29, v53, v54 offset0:8 offset1:74
	s_waitcnt vmcnt(24)
	ds_write2_b32 v29, v55, v56 offset0:140 offset1:206
	s_waitcnt vmcnt(22)
	ds_write2_b32 v30, v57, v58 offset0:16 offset1:82
	s_waitcnt vmcnt(20)
	ds_write2_b32 v30, v59, v60 offset0:148 offset1:214
	s_waitcnt vmcnt(18)
	ds_write2_b32 v31, v61, v62 offset0:24 offset1:90
	s_waitcnt vmcnt(16)
	ds_write2_b32 v31, v63, v64 offset0:156 offset1:222
	s_waitcnt vmcnt(14)
	ds_write2_b32 v32, v65, v66 offset0:32 offset1:98
	s_waitcnt vmcnt(12)
	ds_write2_b32 v32, v67, v68 offset0:164 offset1:230
	s_waitcnt vmcnt(10)
	ds_write2_b32 v33, v69, v70 offset0:40 offset1:106
	s_waitcnt vmcnt(8)
	ds_write2_b32 v33, v71, v72 offset0:172 offset1:238
	s_waitcnt vmcnt(6)
	ds_write2_b32 v34, v48, v49 offset0:48 offset1:114
	s_waitcnt vmcnt(4)
	ds_write2_b32 v34, v73, v74 offset0:180 offset1:246
	s_waitcnt vmcnt(2)
	ds_write2_b32 v35, v75, v76 offset0:56 offset1:122
	s_waitcnt vmcnt(0)
	ds_write2_b32 v35, v77, v78 offset0:188 offset1:254
	s_waitcnt lgkmcnt(0)
	ds_read2_b32 v[36:37], v25 offset0:33 offset1:41
	ds_read2_b32 v[38:39], v25 offset1:8
	ds_read2_b32 v[40:41], v25 offset0:66 offset1:74
	ds_read2_b32 v[42:43], v25 offset0:99 offset1:107
	ds_read2_b32 v[44:45], v25 offset0:132 offset1:140
	ds_read2_b32 v[46:47], v25 offset0:165 offset1:173
	ds_read2_b32 v[48:49], v25 offset0:198 offset1:206
	ds_read2_b32 v[50:51], v25 offset0:231 offset1:239
	v_or_b32_e32 v0, s4, v24
	v_lshl_add_u64 v[52:53], v[12:13], 0, s[2:3]
	v_lshlrev_b32_e32 v0, 12, v0
	s_waitcnt lgkmcnt(6)
	v_cvt_pk_bf16_f32 v18, v38, v36
	s_waitcnt lgkmcnt(4)
	v_cvt_pk_bf16_f32 v19, v40, v42
	s_waitcnt lgkmcnt(2)
	v_cvt_pk_bf16_f32 v20, v44, v46
	s_waitcnt lgkmcnt(0)
	v_cvt_pk_bf16_f32 v21, v48, v50
	v_lshl_add_u64 v[54:55], v[52:53], 0, v[0:1]
	global_store_dwordx4 v[54:55], v[18:21], off
	v_or_b32_e32 v0, s4, v26
	v_lshlrev_b32_e32 v0, 12, v0
	v_cvt_pk_bf16_f32 v18, v39, v37
	v_cvt_pk_bf16_f32 v19, v41, v43
	v_cvt_pk_bf16_f32 v20, v45, v47
	v_cvt_pk_bf16_f32 v21, v49, v51
	ds_read2_b32 v[38:39], v25 offset0:49 offset1:57
	ds_read2_b32 v[40:41], v25 offset0:16 offset1:24
	ds_read2_b32 v[42:43], v25 offset0:82 offset1:90
	ds_read2_b32 v[44:45], v25 offset0:115 offset1:123
	ds_read2_b32 v[46:47], v25 offset0:148 offset1:156
	ds_read2_b32 v[48:49], v25 offset0:181 offset1:189
	ds_read2_b32 v[50:51], v25 offset0:214 offset1:222
	ds_read2_b32 v[54:55], v25 offset0:247 offset1:255
	v_lshl_add_u64 v[36:37], v[52:53], 0, v[0:1]
	v_or_b32_e32 v0, s4, v27
	v_lshlrev_b32_e32 v0, 12, v0
	global_store_dwordx4 v[36:37], v[18:21], off
	v_lshl_add_u64 v[36:37], v[52:53], 0, v[0:1]
	v_or_b32_e32 v0, s4, v28
	s_waitcnt lgkmcnt(6)
	v_cvt_pk_bf16_f32 v18, v40, v38
	s_waitcnt lgkmcnt(4)
	v_cvt_pk_bf16_f32 v19, v42, v44
	s_waitcnt lgkmcnt(2)
	v_cvt_pk_bf16_f32 v20, v46, v48
	s_waitcnt lgkmcnt(0)
	v_cvt_pk_bf16_f32 v21, v50, v54
	v_lshlrev_b32_e32 v0, 12, v0
	global_store_dwordx4 v[36:37], v[18:21], off
	v_lshl_add_u64 v[36:37], v[52:53], 0, v[0:1]
	s_nop 0
	v_cvt_pk_bf16_f32 v18, v41, v39
	v_cvt_pk_bf16_f32 v19, v43, v45
	v_cvt_pk_bf16_f32 v20, v47, v49
	v_cvt_pk_bf16_f32 v21, v51, v55
	global_store_dwordx4 v[36:37], v[18:21], off
	s_waitcnt lgkmcnt(0)

.LBB0_975:
	s_ashr_i32 s2, s6, 31
	s_lshr_b32 s2, s2, 27
	s_add_i32 s2, s6, s2
	s_and_b32 s4, s2, 0x7ffffe0
	s_lshl_b32 s2, s2, 1
	s_sub_i32 s4, s6, s4
	s_and_b32 s6, s2, 0xffffffc0
	s_lshl_b32 s4, s4, 5
	v_or_b32_e32 v20, s6, v22
	s_ashr_i32 s5, s4, 31
	v_ashrrev_i32_e32 v21, 31, v20
	v_or_b32_e32 v38, 2, v20
	v_or_b32_e32 v40, 4, v20
	v_or_b32_e32 v42, 6, v20
	v_or_b32_e32 v44, 8, v20
	v_or_b32_e32 v46, 10, v20
	v_or_b32_e32 v48, 12, v20
	v_or_b32_e32 v50, 14, v20
	v_lshl_add_u64 v[18:19], s[4:5], 2, v[14:15]
	v_lshlrev_b64 v[36:37], 12, v[20:21]
	v_ashrrev_i32_e32 v39, 31, v38
	v_ashrrev_i32_e32 v41, 31, v40
	v_ashrrev_i32_e32 v43, 31, v42
	v_ashrrev_i32_e32 v45, 31, v44
	v_ashrrev_i32_e32 v47, 31, v46
	v_ashrrev_i32_e32 v49, 31, v48
	v_ashrrev_i32_e32 v51, 31, v50
	v_lshl_add_u64 v[36:37], v[18:19], 0, v[36:37]
	v_lshlrev_b64 v[38:39], 12, v[38:39]
	v_lshlrev_b64 v[40:41], 12, v[40:41]
	v_lshlrev_b64 v[42:43], 12, v[42:43]
	v_lshlrev_b64 v[44:45], 12, v[44:45]
	v_lshlrev_b64 v[46:47], 12, v[46:47]
	v_lshlrev_b64 v[48:49], 12, v[48:49]
	v_lshlrev_b64 v[50:51], 12, v[50:51]
	v_lshl_add_u64 v[38:39], v[18:19], 0, v[38:39]
	v_lshl_add_u64 v[40:41], v[18:19], 0, v[40:41]
	v_lshl_add_u64 v[42:43], v[18:19], 0, v[42:43]
	v_lshl_add_u64 v[44:45], v[18:19], 0, v[44:45]
	v_lshl_add_u64 v[46:47], v[18:19], 0, v[46:47]
	v_lshl_add_u64 v[48:49], v[18:19], 0, v[48:49]
	v_lshl_add_u64 v[50:51], v[18:19], 0, v[50:51]
	global_load_dword v0, v[36:37], off
	global_load_dword v52, v[38:39], off
	global_load_dword v53, v[40:41], off
	global_load_dword v54, v[42:43], off
	global_load_dword v55, v[44:45], off
	global_load_dword v56, v[46:47], off
	global_load_dword v57, v[48:49], off
	global_load_dword v58, v[50:51], off
	v_or_b32_e32 v36, 16, v20
	v_ashrrev_i32_e32 v37, 31, v36
	v_or_b32_e32 v38, 18, v20
	v_or_b32_e32 v40, 20, v20
	v_or_b32_e32 v42, 22, v20
	v_or_b32_e32 v44, 24, v20
	v_or_b32_e32 v46, 26, v20
	v_or_b32_e32 v48, 28, v20
	v_or_b32_e32 v50, 30, v20
	v_lshlrev_b64 v[36:37], 12, v[36:37]
	v_ashrrev_i32_e32 v39, 31, v38
	v_ashrrev_i32_e32 v41, 31, v40
	v_ashrrev_i32_e32 v43, 31, v42
	v_ashrrev_i32_e32 v45, 31, v44
	v_ashrrev_i32_e32 v47, 31, v46
	v_ashrrev_i32_e32 v49, 31, v48
	v_ashrrev_i32_e32 v51, 31, v50
	v_lshl_add_u64 v[36:37], v[18:19], 0, v[36:37]
	v_lshlrev_b64 v[38:39], 12, v[38:39]
	v_lshlrev_b64 v[40:41], 12, v[40:41]
	v_lshlrev_b64 v[42:43], 12, v[42:43]
	v_lshlrev_b64 v[44:45], 12, v[44:45]
	v_lshlrev_b64 v[46:47], 12, v[46:47]
	v_lshlrev_b64 v[48:49], 12, v[48:49]
	v_lshlrev_b64 v[50:51], 12, v[50:51]
	v_lshl_add_u64 v[38:39], v[18:19], 0, v[38:39]
	v_lshl_add_u64 v[40:41], v[18:19], 0, v[40:41]
	v_lshl_add_u64 v[42:43], v[18:19], 0, v[42:43]
	v_lshl_add_u64 v[44:45], v[18:19], 0, v[44:45]
	v_lshl_add_u64 v[46:47], v[18:19], 0, v[46:47]
	v_lshl_add_u64 v[48:49], v[18:19], 0, v[48:49]
	v_lshl_add_u64 v[50:51], v[18:19], 0, v[50:51]
	global_load_dword v59, v[36:37], off
	global_load_dword v60, v[38:39], off
	global_load_dword v61, v[40:41], off
	global_load_dword v62, v[42:43], off
	global_load_dword v63, v[44:45], off
	global_load_dword v64, v[46:47], off
	global_load_dword v65, v[48:49], off
	global_load_dword v66, v[50:51], off
	v_or_b32_e32 v36, 32, v20
	v_ashrrev_i32_e32 v37, 31, v36
	v_or_b32_e32 v38, 34, v20
	v_or_b32_e32 v40, 36, v20
	v_or_b32_e32 v42, 38, v20
	v_or_b32_e32 v44, 40, v20
	v_or_b32_e32 v46, 42, v20
	v_or_b32_e32 v48, 44, v20
	v_or_b32_e32 v50, 46, v20
	v_lshlrev_b64 v[36:37], 12, v[36:37]
	v_ashrrev_i32_e32 v39, 31, v38
	v_ashrrev_i32_e32 v41, 31, v40
	v_ashrrev_i32_e32 v43, 31, v42
	v_ashrrev_i32_e32 v45, 31, v44
	v_ashrrev_i32_e32 v47, 31, v46
	v_ashrrev_i32_e32 v49, 31, v48
	v_ashrrev_i32_e32 v51, 31, v50
	v_lshl_add_u64 v[36:37], v[18:19], 0, v[36:37]
	v_lshlrev_b64 v[38:39], 12, v[38:39]
	v_lshlrev_b64 v[40:41], 12, v[40:41]
	v_lshlrev_b64 v[42:43], 12, v[42:43]
	v_lshlrev_b64 v[44:45], 12, v[44:45]
	v_lshlrev_b64 v[46:47], 12, v[46:47]
	v_lshlrev_b64 v[48:49], 12, v[48:49]
	v_lshlrev_b64 v[50:51], 12, v[50:51]
	v_lshl_add_u64 v[38:39], v[18:19], 0, v[38:39]
	v_lshl_add_u64 v[40:41], v[18:19], 0, v[40:41]
	v_lshl_add_u64 v[42:43], v[18:19], 0, v[42:43]
	v_lshl_add_u64 v[44:45], v[18:19], 0, v[44:45]
	v_lshl_add_u64 v[46:47], v[18:19], 0, v[46:47]
	v_lshl_add_u64 v[48:49], v[18:19], 0, v[48:49]
	v_lshl_add_u64 v[50:51], v[18:19], 0, v[50:51]
	global_load_dword v67, v[36:37], off
	global_load_dword v68, v[38:39], off
	global_load_dword v69, v[40:41], off
	global_load_dword v70, v[42:43], off
	global_load_dword v71, v[44:45], off
	global_load_dword v72, v[46:47], off
	global_load_dword v73, v[48:49], off
	global_load_dword v74, v[50:51], off
	v_or_b32_e32 v36, 48, v20
	v_ashrrev_i32_e32 v37, 31, v36
	v_or_b32_e32 v38, 50, v20
	v_or_b32_e32 v40, 52, v20
	v_or_b32_e32 v42, 54, v20
	v_or_b32_e32 v44, 56, v20
	v_or_b32_e32 v46, 58, v20
	v_or_b32_e32 v48, 60, v20
	v_or_b32_e32 v20, 62, v20
	v_lshlrev_b64 v[36:37], 12, v[36:37]
	v_ashrrev_i32_e32 v39, 31, v38
	v_ashrrev_i32_e32 v41, 31, v40
	v_ashrrev_i32_e32 v43, 31, v42
	v_ashrrev_i32_e32 v45, 31, v44
	v_ashrrev_i32_e32 v47, 31, v46
	v_ashrrev_i32_e32 v49, 31, v48
	v_ashrrev_i32_e32 v21, 31, v20
	v_lshl_add_u64 v[36:37], v[18:19], 0, v[36:37]
	v_lshlrev_b64 v[38:39], 12, v[38:39]
	v_lshlrev_b64 v[40:41], 12, v[40:41]
	v_lshlrev_b64 v[42:43], 12, v[42:43]
	v_lshlrev_b64 v[44:45], 12, v[44:45]
	v_lshlrev_b64 v[46:47], 12, v[46:47]
	v_lshlrev_b64 v[48:49], 12, v[48:49]
	v_lshlrev_b64 v[20:21], 12, v[20:21]
	v_lshl_add_u64 v[38:39], v[18:19], 0, v[38:39]
	v_lshl_add_u64 v[40:41], v[18:19], 0, v[40:41]
	v_lshl_add_u64 v[42:43], v[18:19], 0, v[42:43]
	v_lshl_add_u64 v[44:45], v[18:19], 0, v[44:45]
	v_lshl_add_u64 v[46:47], v[18:19], 0, v[46:47]
	v_lshl_add_u64 v[48:49], v[18:19], 0, v[48:49]
	v_lshl_add_u64 v[18:19], v[18:19], 0, v[20:21]
	global_load_dword v20, v[36:37], off
	global_load_dword v21, v[38:39], off
	global_load_dword v50, v[40:41], off
	global_load_dword v51, v[42:43], off
	global_load_dword v75, v[44:45], off
	global_load_dword v76, v[46:47], off
	global_load_dword v77, v[48:49], off
	global_load_dword v78, v[18:19], off
	s_waitcnt vmcnt(30)
	ds_write2_b32 v23, v0, v52 offset1:66
	s_waitcnt vmcnt(28)
	ds_write2_b32 v23, v53, v54 offset0:132 offset1:198
	s_waitcnt vmcnt(26)
	ds_write2_b32 v29, v55, v56 offset0:8 offset1:74
	s_waitcnt vmcnt(24)
	ds_write2_b32 v29, v57, v58 offset0:140 offset1:206
	s_waitcnt vmcnt(22)
	ds_write2_b32 v30, v59, v60 offset0:16 offset1:82
	s_waitcnt vmcnt(20)
	ds_write2_b32 v30, v61, v62 offset0:148 offset1:214
	s_waitcnt vmcnt(18)
	ds_write2_b32 v31, v63, v64 offset0:24 offset1:90
	s_waitcnt vmcnt(16)
	ds_write2_b32 v31, v65, v66 offset0:156 offset1:222
	s_waitcnt vmcnt(14)
	ds_write2_b32 v32, v67, v68 offset0:32 offset1:98
	s_waitcnt vmcnt(12)
	ds_write2_b32 v32, v69, v70 offset0:164 offset1:230
	s_waitcnt vmcnt(10)
	ds_write2_b32 v33, v71, v72 offset0:40 offset1:106
	s_waitcnt vmcnt(8)
	ds_write2_b32 v33, v73, v74 offset0:172 offset1:238
	s_waitcnt vmcnt(6)
	ds_write2_b32 v34, v20, v21 offset0:48 offset1:114
	s_waitcnt vmcnt(4)
	ds_write2_b32 v34, v50, v51 offset0:180 offset1:246
	s_waitcnt vmcnt(2)
	ds_write2_b32 v35, v75, v76 offset0:56 offset1:122
	s_waitcnt vmcnt(0)
	ds_write2_b32 v35, v77, v78 offset0:188 offset1:254
	s_waitcnt lgkmcnt(0)
	ds_read2_b32 v[36:37], v25 offset0:33 offset1:41
	ds_read2_b32 v[38:39], v25 offset1:8
	ds_read2_b32 v[40:41], v25 offset0:66 offset1:74
	ds_read2_b32 v[42:43], v25 offset0:99 offset1:107
	ds_read2_b32 v[44:45], v25 offset0:132 offset1:140
	ds_read2_b32 v[46:47], v25 offset0:165 offset1:173
	ds_read2_b32 v[48:49], v25 offset0:198 offset1:206
	ds_read2_b32 v[50:51], v25 offset0:231 offset1:239
	v_or_b32_e32 v54, s4, v24
	s_ashr_i32 s7, s6, 31
	v_ashrrev_i32_e32 v55, 31, v54
	v_lshl_add_u64 v[52:53], s[6:7], 1, v[16:17]
	v_lshlrev_b64 v[54:55], 11, v[54:55]
	s_waitcnt lgkmcnt(6)
	v_cvt_pk_bf16_f32 v18, v38, v36
	s_waitcnt lgkmcnt(4)
	v_cvt_pk_bf16_f32 v19, v40, v42
	s_waitcnt lgkmcnt(2)
	v_cvt_pk_bf16_f32 v20, v44, v46
	s_waitcnt lgkmcnt(0)
	v_cvt_pk_bf16_f32 v21, v48, v50
	v_lshl_add_u64 v[54:55], v[52:53], 0, v[54:55]
	v_or_b32_e32 v36, s4, v26
	global_store_dwordx4 v[54:55], v[18:21], off
	s_nop 1
	v_cvt_pk_bf16_f32 v18, v39, v37
	v_ashrrev_i32_e32 v37, 31, v36
	v_cvt_pk_bf16_f32 v19, v41, v43
	v_cvt_pk_bf16_f32 v20, v45, v47
	v_cvt_pk_bf16_f32 v21, v49, v51
	v_lshlrev_b64 v[36:37], 11, v[36:37]
	ds_read2_b32 v[38:39], v25 offset0:49 offset1:57
	ds_read2_b32 v[40:41], v25 offset0:16 offset1:24
	ds_read2_b32 v[42:43], v25 offset0:82 offset1:90
	ds_read2_b32 v[44:45], v25 offset0:115 offset1:123
	ds_read2_b32 v[46:47], v25 offset0:148 offset1:156
	ds_read2_b32 v[48:49], v25 offset0:181 offset1:189
	ds_read2_b32 v[50:51], v25 offset0:214 offset1:222
	ds_read2_b32 v[54:55], v25 offset0:247 offset1:255
	v_lshl_add_u64 v[36:37], v[52:53], 0, v[36:37]
	global_store_dwordx4 v[36:37], v[18:21], off
	v_or_b32_e32 v36, s4, v27
	v_ashrrev_i32_e32 v37, 31, v36
	v_lshlrev_b64 v[36:37], 11, v[36:37]
	s_waitcnt lgkmcnt(6)
	v_cvt_pk_bf16_f32 v18, v40, v38
	s_waitcnt lgkmcnt(4)
	v_cvt_pk_bf16_f32 v19, v42, v44
	s_waitcnt lgkmcnt(2)
	v_cvt_pk_bf16_f32 v20, v46, v48
	s_waitcnt lgkmcnt(0)
	v_cvt_pk_bf16_f32 v21, v50, v54
	v_lshl_add_u64 v[36:37], v[52:53], 0, v[36:37]
	global_store_dwordx4 v[36:37], v[18:21], off
	v_or_b32_e32 v36, s4, v28
	v_ashrrev_i32_e32 v37, 31, v36
	v_lshlrev_b64 v[36:37], 11, v[36:37]
	v_cvt_pk_bf16_f32 v18, v41, v39
	v_cvt_pk_bf16_f32 v19, v43, v45
	v_cvt_pk_bf16_f32 v20, v47, v49
	v_cvt_pk_bf16_f32 v21, v51, v55
	v_lshl_add_u64 v[36:37], v[52:53], 0, v[36:37]
	global_store_dwordx4 v[36:37], v[18:21], off
	s_waitcnt lgkmcnt(0)
	s_branch .LBB0_963

.LBB0_1068:
	s_ashr_i32 s2, s6, 31
	s_lshr_b32 s2, s2, 26
	s_add_i32 s2, s6, s2
	s_ashr_i32 s11, s2, 6
	s_andn2_b32 s2, s2, 63
	s_lshl_b32 s3, s11, 11
	v_or_b32_e32 v16, s2, v4
	s_sub_i32 s4, s9, s3
	v_or_b32_e32 v26, 10, v16
	v_or_b32_e32 v28, 12, v16
	v_or_b32_e32 v30, 14, v16
	v_or_b32_e32 v40, 24, v16
	v_or_b32_e32 v42, 26, v16
	v_or_b32_e32 v44, 28, v16
	v_or_b32_e32 v46, 30, v16
	v_ashrrev_i32_e32 v17, 31, v16
	v_or_b32_e32 v18, 2, v16
	v_or_b32_e32 v20, 4, v16
	v_or_b32_e32 v22, 6, v16
	v_or_b32_e32 v24, 8, v16
	v_or_b32_e32 v32, 16, v16
	v_or_b32_e32 v34, 18, v16
	v_or_b32_e32 v36, 20, v16
	v_or_b32_e32 v38, 22, v16
	v_or_b32_e32 v48, 32, v16
	v_or_b32_e32 v50, 34, v16
	v_or_b32_e32 v52, 36, v16
	v_or_b32_e32 v54, 38, v16
	v_or_b32_e32 v56, 40, v16
	v_or_b32_e32 v58, 42, v16
	v_or_b32_e32 v60, 44, v16
	v_or_b32_e32 v62, 46, v16
	v_or_b32_e32 v64, 48, v16
	v_or_b32_e32 v66, 50, v16
	v_or_b32_e32 v68, 52, v16
	v_or_b32_e32 v70, 54, v16
	v_or_b32_e32 v72, 56, v16
	v_or_b32_e32 v74, 58, v16
	v_or_b32_e32 v76, 60, v16
	v_or_b32_e32 v78, 62, v16
	s_ashr_i32 s5, s4, 31
	v_ashrrev_i32_e32 v27, 31, v26
	v_ashrrev_i32_e32 v29, 31, v28
	v_ashrrev_i32_e32 v31, 31, v30
	v_ashrrev_i32_e32 v41, 31, v40
	v_ashrrev_i32_e32 v43, 31, v42
	v_ashrrev_i32_e32 v45, 31, v44
	v_ashrrev_i32_e32 v47, 31, v46
	v_lshlrev_b64 v[16:17], 13, v[16:17]
	v_ashrrev_i32_e32 v19, 31, v18
	v_ashrrev_i32_e32 v21, 31, v20
	v_ashrrev_i32_e32 v23, 31, v22
	v_ashrrev_i32_e32 v25, 31, v24
	v_ashrrev_i32_e32 v33, 31, v32
	v_ashrrev_i32_e32 v35, 31, v34
	v_ashrrev_i32_e32 v37, 31, v36
	v_ashrrev_i32_e32 v39, 31, v38
	v_ashrrev_i32_e32 v49, 31, v48
	v_ashrrev_i32_e32 v51, 31, v50
	v_ashrrev_i32_e32 v53, 31, v52
	v_ashrrev_i32_e32 v55, 31, v54
	v_ashrrev_i32_e32 v57, 31, v56
	v_ashrrev_i32_e32 v59, 31, v58
	v_ashrrev_i32_e32 v61, 31, v60
	v_ashrrev_i32_e32 v63, 31, v62
	v_ashrrev_i32_e32 v65, 31, v64
	v_ashrrev_i32_e32 v67, 31, v66
	v_ashrrev_i32_e32 v69, 31, v68
	v_ashrrev_i32_e32 v71, 31, v70
	v_ashrrev_i32_e32 v73, 31, v72
	v_ashrrev_i32_e32 v75, 31, v74
	v_ashrrev_i32_e32 v77, 31, v76
	v_ashrrev_i32_e32 v79, 31, v78
	v_lshl_add_u64 v[80:81], s[4:5], 2, v[0:1]
	v_lshlrev_b64 v[26:27], 13, v[26:27]
	v_lshlrev_b64 v[28:29], 13, v[28:29]
	v_lshlrev_b64 v[30:31], 13, v[30:31]
	v_lshlrev_b64 v[40:41], 13, v[40:41]
	v_lshlrev_b64 v[42:43], 13, v[42:43]
	v_lshlrev_b64 v[44:45], 13, v[44:45]
	v_lshlrev_b64 v[46:47], 13, v[46:47]
	v_lshlrev_b64 v[18:19], 13, v[18:19]
	v_lshlrev_b64 v[20:21], 13, v[20:21]
	v_lshlrev_b64 v[22:23], 13, v[22:23]
	v_lshlrev_b64 v[24:25], 13, v[24:25]
	v_lshlrev_b64 v[32:33], 13, v[32:33]
	v_lshlrev_b64 v[34:35], 13, v[34:35]
	v_lshlrev_b64 v[36:37], 13, v[36:37]
	v_lshlrev_b64 v[38:39], 13, v[38:39]
	v_lshlrev_b64 v[48:49], 13, v[48:49]
	v_lshlrev_b64 v[50:51], 13, v[50:51]
	v_lshlrev_b64 v[52:53], 13, v[52:53]
	v_lshlrev_b64 v[54:55], 13, v[54:55]
	v_lshlrev_b64 v[56:57], 13, v[56:57]
	v_lshlrev_b64 v[58:59], 13, v[58:59]
	v_lshlrev_b64 v[60:61], 13, v[60:61]
	v_lshlrev_b64 v[62:63], 13, v[62:63]
	v_lshlrev_b64 v[64:65], 13, v[64:65]
	v_lshlrev_b64 v[66:67], 13, v[66:67]
	v_lshlrev_b64 v[68:69], 13, v[68:69]
	v_lshlrev_b64 v[70:71], 13, v[70:71]
	v_lshlrev_b64 v[72:73], 13, v[72:73]
	v_lshlrev_b64 v[74:75], 13, v[74:75]
	v_lshlrev_b64 v[76:77], 13, v[76:77]
	v_lshlrev_b64 v[78:79], 13, v[78:79]
	v_lshl_add_u64 v[16:17], v[80:81], 0, v[16:17]
	v_lshl_add_u64 v[26:27], v[80:81], 0, v[26:27]
	v_lshl_add_u64 v[28:29], v[80:81], 0, v[28:29]
	v_lshl_add_u64 v[30:31], v[80:81], 0, v[30:31]
	v_lshl_add_u64 v[40:41], v[80:81], 0, v[40:41]
	v_lshl_add_u64 v[42:43], v[80:81], 0, v[42:43]
	v_lshl_add_u64 v[44:45], v[80:81], 0, v[44:45]
	v_lshl_add_u64 v[46:47], v[80:81], 0, v[46:47]
	v_lshl_add_u64 v[18:19], v[80:81], 0, v[18:19]
	v_lshl_add_u64 v[20:21], v[80:81], 0, v[20:21]
	v_lshl_add_u64 v[22:23], v[80:81], 0, v[22:23]
	v_lshl_add_u64 v[24:25], v[80:81], 0, v[24:25]
	v_lshl_add_u64 v[32:33], v[80:81], 0, v[32:33]
	v_lshl_add_u64 v[34:35], v[80:81], 0, v[34:35]
	v_lshl_add_u64 v[36:37], v[80:81], 0, v[36:37]
	v_lshl_add_u64 v[38:39], v[80:81], 0, v[38:39]
	v_lshl_add_u64 v[48:49], v[80:81], 0, v[48:49]
	v_lshl_add_u64 v[50:51], v[80:81], 0, v[50:51]
	v_lshl_add_u64 v[52:53], v[80:81], 0, v[52:53]
	v_lshl_add_u64 v[54:55], v[80:81], 0, v[54:55]
	v_lshl_add_u64 v[56:57], v[80:81], 0, v[56:57]
	v_lshl_add_u64 v[58:59], v[80:81], 0, v[58:59]
	v_lshl_add_u64 v[60:61], v[80:81], 0, v[60:61]
	v_lshl_add_u64 v[62:63], v[80:81], 0, v[62:63]
	v_lshl_add_u64 v[64:65], v[80:81], 0, v[64:65]
	v_lshl_add_u64 v[66:67], v[80:81], 0, v[66:67]
	v_lshl_add_u64 v[68:69], v[80:81], 0, v[68:69]
	v_lshl_add_u64 v[70:71], v[80:81], 0, v[70:71]
	v_lshl_add_u64 v[72:73], v[80:81], 0, v[72:73]
	v_lshl_add_u64 v[74:75], v[80:81], 0, v[74:75]
	v_lshl_add_u64 v[76:77], v[80:81], 0, v[76:77]
	v_lshl_add_u64 v[78:79], v[80:81], 0, v[78:79]
	global_load_dword v15, v[16:17], off
	global_load_dword v80, v[18:19], off
	global_load_dword v81, v[20:21], off
	global_load_dword v82, v[22:23], off
	global_load_dword v83, v[24:25], off
	global_load_dword v84, v[26:27], off
	global_load_dword v85, v[28:29], off
	global_load_dword v86, v[30:31], off
	global_load_dword v87, v[32:33], off
	global_load_dword v88, v[34:35], off
	global_load_dword v89, v[36:37], off
	global_load_dword v90, v[38:39], off
	global_load_dword v91, v[40:41], off
	global_load_dword v92, v[42:43], off
	global_load_dword v93, v[44:45], off
	global_load_dword v26, v[46:47], off
	global_load_dword v27, v[48:49], off
	global_load_dword v28, v[50:51], off
	global_load_dword v29, v[52:53], off
	global_load_dword v30, v[54:55], off
	global_load_dword v31, v[56:57], off
	global_load_dword v40, v[58:59], off
	global_load_dword v41, v[60:61], off
	global_load_dword v42, v[62:63], off
	global_load_dword v43, v[64:65], off
	global_load_dword v44, v[66:67], off
	global_load_dword v45, v[68:69], off
	global_load_dword v94, v[70:71], off
	global_load_dword v95, v[72:73], off
	global_load_dword v96, v[74:75], off
	global_load_dword v46, v[76:77], off
	global_load_dword v47, v[78:79], off
	s_mul_i32 s11, s11, 0xff500000
	v_add_u32_e32 v18, s11, v6
	s_ashr_i32 s3, s2, 31
	v_add_u32_e32 v20, 0xb000, v18
	v_add_u32_e32 v22, 0x16000, v18
	v_add_u32_e32 v24, 0x21000, v18
	s_waitcnt vmcnt(30)
	ds_write2_b32 v7, v15, v80 offset1:66
	s_waitcnt vmcnt(28)
	ds_write2_b32 v7, v81, v82 offset0:132 offset1:198
	s_waitcnt vmcnt(26)
	ds_write2_b32 v8, v83, v84 offset0:8 offset1:74
	s_waitcnt vmcnt(24)
	ds_write2_b32 v8, v85, v86 offset0:140 offset1:206
	s_waitcnt vmcnt(22)
	ds_write2_b32 v9, v87, v88 offset0:16 offset1:82
	s_waitcnt vmcnt(20)
	ds_write2_b32 v9, v89, v90 offset0:148 offset1:214
	s_waitcnt vmcnt(18)
	ds_write2_b32 v10, v91, v92 offset0:24 offset1:90
	s_waitcnt vmcnt(16)
	ds_write2_b32 v10, v93, v26 offset0:156 offset1:222
	s_waitcnt vmcnt(14)
	ds_write2_b32 v11, v27, v28 offset0:32 offset1:98
	s_waitcnt vmcnt(12)
	ds_write2_b32 v11, v29, v30 offset0:164 offset1:230
	s_waitcnt vmcnt(10)
	ds_write2_b32 v12, v31, v40 offset0:40 offset1:106
	s_waitcnt vmcnt(8)
	ds_write2_b32 v12, v41, v42 offset0:172 offset1:238
	s_waitcnt vmcnt(6)
	ds_write2_b32 v13, v43, v44 offset0:48 offset1:114
	s_waitcnt vmcnt(4)
	ds_write2_b32 v13, v45, v94 offset0:180 offset1:246
	s_waitcnt vmcnt(2)
	ds_write2_b32 v14, v95, v96 offset0:56 offset1:122
	s_waitcnt vmcnt(0)
	ds_write2_b32 v14, v46, v47 offset0:188 offset1:254
	v_lshl_add_u64 v[16:17], s[2:3], 1, v[2:3]
	v_ashrrev_i32_e32 v21, 31, v20
	v_ashrrev_i32_e32 v23, 31, v22
	v_ashrrev_i32_e32 v25, 31, v24
	s_waitcnt lgkmcnt(0)
	v_lshl_add_u64 v[34:35], v[20:21], 1, v[16:17]
	v_lshl_add_u64 v[36:37], v[22:23], 1, v[16:17]
	v_lshl_add_u64 v[38:39], v[24:25], 1, v[16:17]
	ds_read2_b32 v[20:21], v5 offset0:33 offset1:41
	ds_read2_b32 v[22:23], v5 offset1:8
	ds_read2_b32 v[24:25], v5 offset0:66 offset1:74
	ds_read2_b32 v[26:27], v5 offset0:99 offset1:107
	ds_read2_b32 v[28:29], v5 offset0:132 offset1:140
	ds_read2_b32 v[30:31], v5 offset0:165 offset1:173
	ds_read2_b32 v[40:41], v5 offset0:198 offset1:206
	ds_read2_b32 v[42:43], v5 offset0:231 offset1:239
	ds_read2_b32 v[44:45], v5 offset0:49 offset1:57
	ds_read2_b32 v[46:47], v5 offset0:16 offset1:24
	ds_read2_b32 v[48:49], v5 offset0:82 offset1:90
	ds_read2_b32 v[50:51], v5 offset0:115 offset1:123
	ds_read2_b32 v[52:53], v5 offset0:148 offset1:156
	ds_read2_b32 v[54:55], v5 offset0:181 offset1:189
	ds_read2_b32 v[56:57], v5 offset0:214 offset1:222
	ds_read2_b32 v[58:59], v5 offset0:247 offset1:255
	v_ashrrev_i32_e32 v19, 31, v18
	v_lshl_add_u64 v[32:33], v[18:19], 1, v[16:17]
	s_waitcnt lgkmcnt(14)
	v_cvt_pk_bf16_f32 v16, v22, v20
	s_waitcnt lgkmcnt(12)
	v_cvt_pk_bf16_f32 v17, v24, v26
	s_waitcnt lgkmcnt(10)
	v_cvt_pk_bf16_f32 v18, v28, v30
	s_waitcnt lgkmcnt(8)
	v_cvt_pk_bf16_f32 v19, v40, v42
	v_cvt_pk_bf16_f32 v20, v23, v21
	v_cvt_pk_bf16_f32 v21, v25, v27
	v_cvt_pk_bf16_f32 v22, v29, v31
	v_cvt_pk_bf16_f32 v23, v41, v43
	s_waitcnt lgkmcnt(6)
	v_cvt_pk_bf16_f32 v24, v46, v44
	s_waitcnt lgkmcnt(4)
	v_cvt_pk_bf16_f32 v25, v48, v50
	s_waitcnt lgkmcnt(2)
	v_cvt_pk_bf16_f32 v26, v52, v54
	s_waitcnt lgkmcnt(0)
	v_cvt_pk_bf16_f32 v27, v56, v58
	v_cvt_pk_bf16_f32 v28, v47, v45
	v_cvt_pk_bf16_f32 v29, v49, v51
	v_cvt_pk_bf16_f32 v30, v53, v55
	v_cvt_pk_bf16_f32 v31, v57, v59
	global_store_dwordx4 v[32:33], v[16:19], off
	global_store_dwordx4 v[34:35], v[20:23], off
	global_store_dwordx4 v[36:37], v[24:27], off
	global_store_dwordx4 v[38:39], v[28:31], off
	s_waitcnt lgkmcnt(0)
	s_add_i32 s6, s6, s7
	s_add_i32 s9, s9, s10
	s_cmpk_lt_i32 s6, 0x1600
	v_add_u32_e32 v6, s8, v6
	s_cbranch_scc1 .LBB0_1068

.LBB0_1729:
	s_andn2_b64 vcc, exec, s[14:15]
	s_cbranch_vccnz .LBB0_1726
	s_add_i32 s2, s0, 0xffffe000
	s_lshl_b64 s[14:15], s[2:3], 13
	v_lshl_add_u64 v[118:119], v[58:59], 0, s[14:15]
	v_add_co_u32_e32 v114, vcc, 0x1000000, v118
	s_nop 1
	v_addc_co_u32_e32 v115, vcc, 0, v119, vcc
	global_load_dwordx4 v[32:35], v[114:115], off
	v_add_co_u32_e32 v116, vcc, 0x2000000, v118
	s_nop 1
	v_addc_co_u32_e32 v117, vcc, 0, v119, vcc
	v_add_co_u32_e32 v120, vcc, 0x3000000, v118
	s_nop 1
	v_addc_co_u32_e32 v121, vcc, 0, v119, vcc
	global_load_dwordx4 v[36:39], v[118:119], off
	global_load_dwordx4 v[44:47], v[118:119], off offset:1024
	global_load_dwordx4 v[52:55], v[114:115], off offset:1024
	global_load_dwordx4 v[40:43], v[120:121], off
	global_load_dwordx4 v[48:51], v[116:117], off
	global_load_dwordx4 v[78:81], v[116:117], off offset:1024
	global_load_dwordx4 v[82:85], v[120:121], off offset:1024
	global_load_dwordx4 v[86:89], v[118:119], off offset:2048
	global_load_dwordx4 v[90:93], v[118:119], off offset:3072
	global_load_dwordx4 v[94:97], v[114:115], off offset:2048
	global_load_dwordx4 v[98:101], v[116:117], off offset:2048
	global_load_dwordx4 v[102:105], v[120:121], off offset:2048
	global_load_dwordx4 v[106:109], v[114:115], off offset:3072
	global_load_dwordx4 v[110:113], v[116:117], off offset:3072
	s_nop 0
	global_load_dwordx4 v[114:117], v[120:121], off offset:3072
	v_add_co_u32_e32 v154, vcc, s16, v118
	s_waitcnt vmcnt(0)
	v_pk_add_f32 v[34:35], v[38:39], v[34:35]
	v_addc_co_u32_e32 v155, vcc, 0, v119, vcc
	v_add_co_u32_e32 v162, vcc, s1, v118
	v_pk_add_f32 v[32:33], v[36:37], v[32:33]
	s_nop 0
	v_addc_co_u32_e32 v163, vcc, 0, v119, vcc
	v_add_co_u32_e32 v170, vcc, s5, v118
	v_pk_add_f32 v[36:37], v[46:47], v[54:55]
	s_nop 0
	v_addc_co_u32_e32 v171, vcc, 0, v119, vcc
	v_add_co_u32_e32 v178, vcc, s17, v118
	v_pk_add_f32 v[38:39], v[44:45], v[52:53]
	s_nop 0
	v_addc_co_u32_e32 v179, vcc, 0, v119, vcc
	global_load_dwordx4 v[118:121], v[154:155], off
	global_load_dwordx4 v[122:125], v[162:163], off
	global_load_dwordx4 v[126:129], v[170:171], off
	global_load_dwordx4 v[130:133], v[178:179], off
	global_load_dwordx4 v[134:137], v[154:155], off offset:1024
	global_load_dwordx4 v[138:141], v[162:163], off offset:1024
	global_load_dwordx4 v[142:145], v[170:171], off offset:1024
	global_load_dwordx4 v[146:149], v[178:179], off offset:1024
	global_load_dwordx4 v[150:153], v[154:155], off offset:2048
	s_nop 0
	global_load_dwordx4 v[154:157], v[154:155], off offset:3072
	s_nop 0
	global_load_dwordx4 v[158:161], v[162:163], off offset:2048
	s_nop 0
	global_load_dwordx4 v[162:165], v[162:163], off offset:3072
	s_nop 0
	global_load_dwordx4 v[166:169], v[170:171], off offset:2048
	s_nop 0
	global_load_dwordx4 v[170:173], v[170:171], off offset:3072
	s_nop 0
	global_load_dwordx4 v[174:177], v[178:179], off offset:2048
	s_nop 0
	global_load_dwordx4 v[178:181], v[178:179], off offset:3072
	v_pk_add_f32 v[42:43], v[50:51], v[42:43]
	v_pk_add_f32 v[40:41], v[48:49], v[40:41]
	v_pk_add_f32 v[44:45], v[80:81], v[84:85]
	v_pk_add_f32 v[46:47], v[78:79], v[82:83]
	v_pk_add_f32 v[34:35], v[34:35], v[42:43]
	v_pk_add_f32 v[32:33], v[32:33], v[40:41]
	v_pk_add_f32 v[36:37], v[36:37], v[44:45]
	v_pk_add_f32 v[38:39], v[38:39], v[46:47]
	v_pk_add_f32 v[30:31], v[30:31], v[34:35]
	v_pk_add_f32 v[28:29], v[28:29], v[32:33]
	v_pk_add_f32 v[26:27], v[26:27], v[36:37]
	v_pk_add_f32 v[24:25], v[24:25], v[38:39]
	v_mov_b32_e32 v34, v29
	v_mov_b32_e32 v35, v25
	v_mov_b32_e32 v38, v31
	v_mov_b32_e32 v39, v27
	v_mov_b32_e32 v32, v28
	v_mov_b32_e32 v33, v24
	v_mov_b32_e32 v36, v30
	v_mov_b32_e32 v37, v26
	v_pk_mul_f32 v[34:35], v[34:35], v[34:35]
	v_pk_mul_f32 v[38:39], v[38:39], v[38:39]
	v_pk_fma_f32 v[32:33], v[32:33], v[32:33], v[34:35]
	v_pk_fma_f32 v[34:35], v[36:37], v[36:37], v[38:39]
	v_pk_add_f32 v[36:37], v[86:87], v[94:95]
	v_pk_add_f32 v[32:33], v[32:33], v[34:35]
	v_pk_add_f32 v[34:35], v[88:89], v[96:97]
	v_pk_add_f32 v[38:39], v[100:101], v[104:105]
	v_pk_add_f32 v[40:41], v[98:99], v[102:103]
	v_pk_add_f32 v[34:35], v[34:35], v[38:39]
	v_pk_add_f32 v[36:37], v[36:37], v[40:41]
	v_pk_add_f32 v[22:23], v[22:23], v[34:35]
	v_pk_add_f32 v[20:21], v[20:21], v[36:37]
	v_pk_mul_f32 v[34:35], v[22:23], v[22:23]
	v_pk_mul_f32 v[36:37], v[20:21], v[20:21]
	v_pk_add_f32 v[42:43], v[110:111], v[114:115]
	v_pk_mov_b32 v[38:39], v[36:37], v[34:35] op_sel:[1,0]
	v_mov_b32_e32 v37, v35
	v_pk_add_f32 v[34:35], v[38:39], v[36:37]
	v_pk_add_f32 v[38:39], v[90:91], v[106:107]
	v_pk_add_f32 v[36:37], v[92:93], v[108:109]
	v_pk_add_f32 v[40:41], v[112:113], v[116:117]
	v_pk_add_f32 v[38:39], v[38:39], v[42:43]
	v_pk_add_f32 v[36:37], v[36:37], v[40:41]
	v_pk_add_f32 v[16:17], v[16:17], v[38:39]
	v_pk_add_f32 v[18:19], v[18:19], v[36:37]
	v_pk_add_f32 v[32:33], v[32:33], v[32:33] op_sel:[0,1] op_sel_hi:[1,0]
	v_pk_add_f32 v[34:35], v[34:35], v[34:35] op_sel:[0,1] op_sel_hi:[1,0]
	v_cmp_lt_i32_e32 vcc, v74, v73
	s_waitcnt vmcnt(14)
	v_pk_add_f32 v[38:39], v[118:119], v[122:123]
	v_pk_add_f32 v[36:37], v[120:121], v[124:125]
	s_waitcnt vmcnt(12)
	v_pk_add_f32 v[42:43], v[126:127], v[130:131]
	v_pk_add_f32 v[40:41], v[128:129], v[132:133]
	v_pk_add_f32 v[38:39], v[38:39], v[42:43]
	v_pk_add_f32 v[36:37], v[36:37], v[40:41]
	v_pk_add_f32 v[12:13], v[12:13], v[38:39]
	v_pk_add_f32 v[14:15], v[14:15], v[36:37]
	v_mul_f32_e32 v36, v12, v12
	v_mul_f32_e32 v37, v13, v13
	v_mov_b32_e32 v33, v36
	v_mov_b32_e32 v35, v37
	v_pk_add_f32 v[32:33], v[32:33], v[34:35]
	v_mul_f32_e32 v34, v17, v17
	v_mul_f32_e32 v36, v19, v19
	v_mul_f32_e32 v38, v14, v14
	v_mul_f32_e32 v39, v15, v15
	v_pk_fma_f32 v[34:35], v[16:17], v[16:17], v[34:35] op_sel_hi:[1,1,0]
	v_pk_fma_f32 v[36:37], v[18:19], v[18:19], v[36:37] op_sel_hi:[1,1,0]
	v_mov_b32_e32 v35, v38
	v_mov_b32_e32 v37, v39
	v_pk_add_f32 v[34:35], v[34:35], v[36:37]
	s_waitcnt vmcnt(10)
	v_pk_add_f32 v[36:37], v[134:135], v[138:139]
	v_pk_add_f32 v[32:33], v[32:33], v[34:35]
	v_pk_add_f32 v[34:35], v[136:137], v[140:141]
	s_waitcnt vmcnt(8)
	v_pk_add_f32 v[38:39], v[144:145], v[148:149]
	v_pk_add_f32 v[40:41], v[142:143], v[146:147]
	v_pk_add_f32 v[34:35], v[34:35], v[38:39]
	v_pk_add_f32 v[36:37], v[36:37], v[40:41]
	v_pk_add_f32 v[10:11], v[10:11], v[34:35]
	v_pk_add_f32 v[8:9], v[8:9], v[36:37]
	v_pk_mul_f32 v[34:35], v[10:11], v[10:11]
	v_pk_mul_f32 v[36:37], v[8:9], v[8:9]
	s_waitcnt vmcnt(1)
	v_pk_add_f32 v[42:43], v[166:167], v[174:175]
	v_pk_mov_b32 v[38:39], v[36:37], v[34:35] op_sel:[1,0]
	v_mov_b32_e32 v37, v35
	v_pk_add_f32 v[34:35], v[38:39], v[36:37]
	v_pk_add_f32 v[38:39], v[150:151], v[158:159]
	v_pk_add_f32 v[36:37], v[152:153], v[160:161]
	v_pk_add_f32 v[40:41], v[168:169], v[176:177]
	v_pk_add_f32 v[38:39], v[38:39], v[42:43]
	v_pk_add_f32 v[36:37], v[36:37], v[40:41]
	v_pk_add_f32 v[4:5], v[4:5], v[38:39]
	v_pk_add_f32 v[38:39], v[154:155], v[162:163]
	s_waitcnt vmcnt(0)
	v_pk_add_f32 v[42:43], v[170:171], v[178:179]
	v_pk_add_f32 v[6:7], v[6:7], v[36:37]
	v_pk_add_f32 v[36:37], v[156:157], v[164:165]
	v_pk_add_f32 v[40:41], v[172:173], v[180:181]
	v_pk_add_f32 v[38:39], v[38:39], v[42:43]
	v_pk_add_f32 v[36:37], v[36:37], v[40:41]
	v_pk_add_f32 v[0:1], v[0:1], v[38:39]
	v_pk_add_f32 v[2:3], v[2:3], v[36:37]
	v_mul_f32_e32 v36, v0, v0
	v_mul_f32_e32 v37, v1, v1
	v_pk_add_f32 v[32:33], v[32:33], v[32:33] op_sel:[0,1] op_sel_hi:[1,0]
	v_pk_add_f32 v[34:35], v[34:35], v[34:35] op_sel:[0,1] op_sel_hi:[1,0]
	v_mov_b32_e32 v33, v36
	v_mov_b32_e32 v35, v37
	v_pk_add_f32 v[32:33], v[32:33], v[34:35]
	v_mul_f32_e32 v34, v5, v5
	v_mul_f32_e32 v36, v7, v7
	v_mul_f32_e32 v38, v2, v2
	v_mul_f32_e32 v39, v3, v3
	v_pk_fma_f32 v[34:35], v[4:5], v[4:5], v[34:35] op_sel_hi:[1,1,0]
	v_pk_fma_f32 v[36:37], v[6:7], v[6:7], v[36:37] op_sel_hi:[1,1,0]
	v_mov_b32_e32 v35, v38
	v_mov_b32_e32 v37, v39
	v_pk_add_f32 v[34:35], v[34:35], v[36:37]
	s_nop 0
	v_pk_add_f32 v[32:33], v[32:33], v[34:35]
	s_nop 0
	v_add_f32_e32 v32, v32, v33
	v_cndmask_b32_e32 v33, v72, v74, vcc
	v_lshlrev_b32_e32 v33, 2, v33
	ds_bpermute_b32 v33, v33, v32
	v_cmp_lt_i32_e32 vcc, v75, v73
	s_waitcnt lgkmcnt(0)
	v_add_f32_e32 v32, v32, v33
	v_cndmask_b32_e32 v33, v72, v75, vcc
	v_lshlrev_b32_e32 v33, 2, v33
	ds_bpermute_b32 v33, v33, v32
	v_cmp_lt_i32_e32 vcc, v76, v73
	s_waitcnt lgkmcnt(0)
	v_add_f32_e32 v32, v32, v33
	v_cndmask_b32_e32 v33, v72, v76, vcc
	v_lshlrev_b32_e32 v33, 2, v33
	ds_bpermute_b32 v33, v33, v32
	s_waitcnt lgkmcnt(0)
	v_add_f32_e32 v32, v32, v33
	v_xor_b32_e32 v33, 8, v72
	v_cmp_lt_i32_e32 vcc, v33, v73
	s_nop 1
	v_cndmask_b32_e32 v33, v72, v33, vcc
	v_lshlrev_b32_e32 v33, 2, v33
	ds_bpermute_b32 v33, v33, v32
	s_waitcnt lgkmcnt(0)
	v_add_f32_e32 v32, v32, v33
	v_xor_b32_e32 v33, 16, v72
	v_cmp_lt_i32_e32 vcc, v33, v73
	s_nop 1
	v_cndmask_b32_e32 v33, v72, v33, vcc
	v_lshlrev_b32_e32 v33, 2, v33
	ds_bpermute_b32 v33, v33, v32
	s_waitcnt lgkmcnt(0)
	v_add_f32_e32 v32, v32, v33
	v_xor_b32_e32 v33, 32, v72
	v_cmp_lt_i32_e32 vcc, v33, v73
	s_nop 1
	v_cndmask_b32_e32 v33, v72, v33, vcc
	v_lshlrev_b32_e32 v33, 2, v33
	ds_bpermute_b32 v33, v33, v32
	s_waitcnt lgkmcnt(0)
	v_add_f32_e32 v32, v32, v33
	s_branch .LBB0_1726
